# GDN prep: q/k/v short-conv loops merged+unrolled, 90 LDS reads with immediate offsets through an 8-quad ring
# speedup vs baseline: 1.0198x; 1.0038x over previous
; DI void unpack8(u32x4 v, float* o) { o[0] = lo16(v.x); o[1] = hi16(v.x); o[2] = lo16(v.y); o[3] = hi16(v.y); o[4] = lo16(v.z); o[5] = hi16(v.z); o[6] = lo16(v.w); o[7] = hi16(v.w); }
; DI float siluf(float x) { return x * __builtin_amdgcn_rcpf(1.f + __expf(-x)); }
; DI void gdn_conv16(const bf16_t* raw, const float* cw, int ti, int cch, float* out) {
; #pragma unroll
;     for (int e = 0; e < 16; ++e) out[e] = 0.f;
; #pragma unroll 1
;     for (int j = 0; j < 5; ++j) {
;         const bf16_t* rp = raw + (ti + j) * 392 + cch;
;         float xv[16];
;         unpack8(*(const u32x4*)rp, xv); unpack8(*(const u32x4*)(rp + 8), xv + 8);
;         const float* w = cw + j * 384 + cch;
; #pragma unroll
;         for (int e4 = 0; e4 < 4; ++e4) { const f32x4 wv = *(const f32x4*)(w + 4 * e4);
; #pragma unroll
;             for (int e = 0; e < 4; ++e) out[4 * e4 + e] += wv[e] * xv[4 * e4 + e]; }
;     }
; #pragma unroll
;     for (int e = 0; e < 16; ++e) out[e] = siluf(out[e]);
; }
; DI void gdn_prep_item(const P& p, int l, int item, unsigned char* smem) {
;     ...
;     float xq[16], xk[16], xv[16];
;     gdn_conv16(raw, sCW, ti, 0 + 16 * sub, xq);
;     gdn_conv16(raw, sCW, ti, 128 + 16 * sub, xk);
;     gdn_conv16(raw, sCW, ti, 256 + 16 * sub, xv);
.LBB0_314:
	s_or_b64 exec, exec, s[0:1]
	v_and_b32_e32 v80, 7, v88
	v_mul_lo_u32 v0, v91, s76
	v_lshl_add_u32 v48, v80, 6, 0
	v_lshl_add_u32 v32, v80, 5, v0
	v_mov_b32_e32 v14, 0
	s_mov_b32 s0, 5
	v_add_u32_e32 v16, 0, v32
	v_mov_b32_e32 v17, v48
	v_mov_b32_e32 v15, v14
	v_mov_b32_e32 v2, v14
	v_mov_b32_e32 v3, v14
	v_mov_b32_e32 v4, v14
	v_mov_b32_e32 v5, v14
	v_mov_b32_e32 v6, v14
	v_mov_b32_e32 v7, v14
	v_mov_b32_e32 v8, v14
	v_mov_b32_e32 v9, v14
	v_mov_b32_e32 v10, v14
	v_mov_b32_e32 v11, v14
	v_mov_b32_e32 v0, v14
	v_mov_b32_e32 v1, v14
	v_mov_b32_e32 v12, v14
	v_mov_b32_e32 v13, v14
	s_waitcnt lgkmcnt(0)
	s_barrier
	v_add_u32_e32 v64, s45, v32
	v_add_u32_e32 v63, s45, v48
	v_add_u32_e32 v63, 0x1cb00, v63
	ds_read_b128 v[228:231], v63 offset:0
	ds_read_b128 v[232:235], v64 offset:0
	ds_read_b128 v[236:239], v63 offset:16
	ds_read_b128 v[240:243], v63 offset:32
	ds_read_b128 v[244:247], v64 offset:16
	ds_read_b128 v[248:251], v63 offset:48
	ds_read_b128 v[48:51], v63 offset:1536
	ds_read_b128 v[52:55], v64 offset:784
	v_mov_b32_e32 v0, 0
	v_mov_b32_e32 v1, 0
	v_mov_b32_e32 v2, 0
	v_mov_b32_e32 v3, 0
	v_mov_b32_e32 v4, 0
	v_mov_b32_e32 v5, 0
	v_mov_b32_e32 v6, 0
	v_mov_b32_e32 v7, 0
	v_mov_b32_e32 v8, 0
	v_mov_b32_e32 v9, 0
	v_mov_b32_e32 v10, 0
	v_mov_b32_e32 v11, 0
	v_mov_b32_e32 v12, 0
	v_mov_b32_e32 v13, 0
	v_mov_b32_e32 v14, 0
	v_mov_b32_e32 v15, 0
	v_mov_b32_e32 v16, 0
	v_mov_b32_e32 v17, 0
	v_mov_b32_e32 v18, 0
	v_mov_b32_e32 v19, 0
	v_mov_b32_e32 v20, 0
	v_mov_b32_e32 v21, 0
	v_mov_b32_e32 v22, 0
	v_mov_b32_e32 v23, 0
	v_mov_b32_e32 v24, 0
	v_mov_b32_e32 v25, 0
	v_mov_b32_e32 v26, 0
	v_mov_b32_e32 v27, 0
	v_mov_b32_e32 v28, 0
	v_mov_b32_e32 v29, 0
	v_mov_b32_e32 v30, 0
	v_mov_b32_e32 v31, 0
	v_mov_b32_e32 v32, 0
	v_mov_b32_e32 v33, 0
	v_mov_b32_e32 v34, 0
	v_mov_b32_e32 v35, 0
	v_mov_b32_e32 v36, 0
	v_mov_b32_e32 v37, 0
	v_mov_b32_e32 v38, 0
	v_mov_b32_e32 v39, 0
	v_mov_b32_e32 v40, 0
	v_mov_b32_e32 v41, 0
	v_mov_b32_e32 v42, 0
	v_mov_b32_e32 v43, 0
	v_mov_b32_e32 v44, 0
	v_mov_b32_e32 v45, 0
	v_mov_b32_e32 v46, 0
	v_mov_b32_e32 v47, 0
	s_waitcnt lgkmcnt(6)
	v_lshlrev_b32_e32 v56, 16, v232
	v_and_b32_e32 v57, 0xffff0000, v232
	v_lshlrev_b32_e32 v58, 16, v233
	v_and_b32_e32 v59, 0xffff0000, v233
	v_fma_f32 v14, v228, v56, v14
	v_fma_f32 v12, v229, v57, v12
	v_fma_f32 v15, v230, v58, v15
	v_fma_f32 v13, v231, v59, v13
	ds_read_b128 v[228:231], v63 offset:1552
	s_waitcnt lgkmcnt(6)
	v_lshlrev_b32_e32 v60, 16, v234
	v_and_b32_e32 v61, 0xffff0000, v234
	v_pk_fma_f32 v[0:1], v[236:237], v[60:61], v[0:1]
	v_lshlrev_b32_e32 v56, 16, v235
	v_and_b32_e32 v57, 0xffff0000, v235
	v_pk_fma_f32 v[10:11], v[238:239], v[56:57], v[10:11]
	ds_read_b128 v[232:235], v63 offset:1568
	ds_read_b128 v[236:239], v64 offset:800
	s_waitcnt lgkmcnt(6)
	v_lshlrev_b32_e32 v58, 16, v244
	v_and_b32_e32 v59, 0xffff0000, v244
	v_pk_fma_f32 v[8:9], v[240:241], v[58:59], v[8:9]
	v_lshlrev_b32_e32 v60, 16, v245
	v_and_b32_e32 v61, 0xffff0000, v245
	v_pk_fma_f32 v[6:7], v[242:243], v[60:61], v[6:7]
	ds_read_b128 v[240:243], v63 offset:1584
	s_waitcnt lgkmcnt(6)
	v_lshlrev_b32_e32 v56, 16, v246
	v_and_b32_e32 v57, 0xffff0000, v246
	v_pk_fma_f32 v[4:5], v[248:249], v[56:57], v[4:5]
	v_lshlrev_b32_e32 v58, 16, v247
	v_and_b32_e32 v59, 0xffff0000, v247
	v_pk_fma_f32 v[2:3], v[250:251], v[58:59], v[2:3]
	ds_read_b128 v[244:247], v63 offset:3072
	ds_read_b128 v[248:251], v64 offset:1568
	s_waitcnt lgkmcnt(6)
	v_lshlrev_b32_e32 v60, 16, v52
	v_and_b32_e32 v61, 0xffff0000, v52
	v_lshlrev_b32_e32 v56, 16, v53
	v_and_b32_e32 v57, 0xffff0000, v53
	v_fma_f32 v14, v48, v60, v14
	v_fma_f32 v12, v49, v61, v12
	v_fma_f32 v15, v50, v56, v15
	v_fma_f32 v13, v51, v57, v13
	ds_read_b128 v[48:51], v63 offset:3088
	s_waitcnt lgkmcnt(6)
	v_lshlrev_b32_e32 v58, 16, v54
	v_and_b32_e32 v59, 0xffff0000, v54
	v_pk_fma_f32 v[0:1], v[228:229], v[58:59], v[0:1]
	v_lshlrev_b32_e32 v60, 16, v55
	v_and_b32_e32 v61, 0xffff0000, v55
	v_pk_fma_f32 v[10:11], v[230:231], v[60:61], v[10:11]
	ds_read_b128 v[52:55], v63 offset:3104
	ds_read_b128 v[228:231], v64 offset:1584
	s_waitcnt lgkmcnt(6)
	v_lshlrev_b32_e32 v56, 16, v236
	v_and_b32_e32 v57, 0xffff0000, v236
	v_pk_fma_f32 v[8:9], v[232:233], v[56:57], v[8:9]
	v_lshlrev_b32_e32 v58, 16, v237
	v_and_b32_e32 v59, 0xffff0000, v237
	v_pk_fma_f32 v[6:7], v[234:235], v[58:59], v[6:7]
	ds_read_b128 v[232:235], v63 offset:3120
	s_waitcnt lgkmcnt(6)
	v_lshlrev_b32_e32 v60, 16, v238
	v_and_b32_e32 v61, 0xffff0000, v238
	v_pk_fma_f32 v[4:5], v[240:241], v[60:61], v[4:5]
	v_lshlrev_b32_e32 v56, 16, v239
	v_and_b32_e32 v57, 0xffff0000, v239
	v_pk_fma_f32 v[2:3], v[242:243], v[56:57], v[2:3]
	ds_read_b128 v[236:239], v63 offset:4608
	ds_read_b128 v[240:243], v64 offset:2352
	s_waitcnt lgkmcnt(6)
	v_lshlrev_b32_e32 v58, 16, v248
	v_and_b32_e32 v59, 0xffff0000, v248
	v_lshlrev_b32_e32 v60, 16, v249
	v_and_b32_e32 v61, 0xffff0000, v249
	v_fma_f32 v14, v244, v58, v14
	v_fma_f32 v12, v245, v59, v12
	v_fma_f32 v15, v246, v60, v15
	v_fma_f32 v13, v247, v61, v13
	ds_read_b128 v[244:247], v63 offset:4624
	s_waitcnt lgkmcnt(6)
	v_lshlrev_b32_e32 v56, 16, v250
	v_and_b32_e32 v57, 0xffff0000, v250
	v_pk_fma_f32 v[0:1], v[48:49], v[56:57], v[0:1]
	v_lshlrev_b32_e32 v58, 16, v251
	v_and_b32_e32 v59, 0xffff0000, v251
	v_pk_fma_f32 v[10:11], v[50:51], v[58:59], v[10:11]
	ds_read_b128 v[248:251], v63 offset:4640
	ds_read_b128 v[48:51], v64 offset:2368
	s_waitcnt lgkmcnt(6)
	v_lshlrev_b32_e32 v60, 16, v228
	v_and_b32_e32 v61, 0xffff0000, v228
	v_pk_fma_f32 v[8:9], v[52:53], v[60:61], v[8:9]
	v_lshlrev_b32_e32 v56, 16, v229
	v_and_b32_e32 v57, 0xffff0000, v229
	v_pk_fma_f32 v[6:7], v[54:55], v[56:57], v[6:7]
	ds_read_b128 v[52:55], v63 offset:4656
	s_waitcnt lgkmcnt(6)
; DI void unpack8(u32x4 v, float* o) { o[0] = lo16(v.x); o[1] = hi16(v.x); o[2] = lo16(v.y); o[3] = hi16(v.y); o[4] = lo16(v.z); o[5] = hi16(v.z); o[6] = lo16(v.w); o[7] = hi16(v.w); }
; DI void gdn_conv16(const bf16_t* raw, const float* cw, int ti, int cch, float* out) {
; #pragma unroll
;     for (int e = 0; e < 16; ++e) out[e] = 0.f;
; #pragma unroll 1
;     for (int j = 0; j < 5; ++j) {
;         const bf16_t* rp = raw + (ti + j) * 392 + cch;
;         float xv[16];
;         unpack8(*(const u32x4*)rp, xv); unpack8(*(const u32x4*)(rp + 8), xv + 8);
;         const float* w = cw + j * 384 + cch;
; #pragma unroll
;         for (int e4 = 0; e4 < 4; ++e4) { const f32x4 wv = *(const f32x4*)(w + 4 * e4);
; #pragma unroll
;             for (int e = 0; e < 4; ++e) out[4 * e4 + e] += wv[e] * xv[4 * e4 + e]; }
;     }
	v_lshlrev_b32_e32 v58, 16, v230
	v_and_b32_e32 v59, 0xffff0000, v230
	v_pk_fma_f32 v[4:5], v[232:233], v[58:59], v[4:5]
	v_lshlrev_b32_e32 v60, 16, v231
	v_and_b32_e32 v61, 0xffff0000, v231
	v_pk_fma_f32 v[2:3], v[234:235], v[60:61], v[2:3]
	ds_read_b128 v[228:231], v63 offset:6144
	ds_read_b128 v[232:235], v64 offset:3136
	s_waitcnt lgkmcnt(6)
	v_lshlrev_b32_e32 v56, 16, v240
	v_and_b32_e32 v57, 0xffff0000, v240
	v_lshlrev_b32_e32 v58, 16, v241
	v_and_b32_e32 v59, 0xffff0000, v241
	v_fma_f32 v14, v236, v56, v14
	v_fma_f32 v12, v237, v57, v12
	v_fma_f32 v15, v238, v58, v15
	v_fma_f32 v13, v239, v59, v13
	ds_read_b128 v[236:239], v63 offset:6160
	s_waitcnt lgkmcnt(6)
	v_lshlrev_b32_e32 v60, 16, v242
	v_and_b32_e32 v61, 0xffff0000, v242
	v_pk_fma_f32 v[0:1], v[244:245], v[60:61], v[0:1]
	v_lshlrev_b32_e32 v56, 16, v243
	v_and_b32_e32 v57, 0xffff0000, v243
	v_pk_fma_f32 v[10:11], v[246:247], v[56:57], v[10:11]
	ds_read_b128 v[240:243], v63 offset:6176
	ds_read_b128 v[244:247], v64 offset:3152
	s_waitcnt lgkmcnt(6)
	v_lshlrev_b32_e32 v58, 16, v48
	v_and_b32_e32 v59, 0xffff0000, v48
	v_pk_fma_f32 v[8:9], v[248:249], v[58:59], v[8:9]
	v_lshlrev_b32_e32 v60, 16, v49
	v_and_b32_e32 v61, 0xffff0000, v49
	v_pk_fma_f32 v[6:7], v[250:251], v[60:61], v[6:7]
	ds_read_b128 v[248:251], v63 offset:6192
	s_waitcnt lgkmcnt(6)
	v_lshlrev_b32_e32 v56, 16, v50
	v_and_b32_e32 v57, 0xffff0000, v50
	v_pk_fma_f32 v[4:5], v[52:53], v[56:57], v[4:5]
	v_lshlrev_b32_e32 v58, 16, v51
	v_and_b32_e32 v59, 0xffff0000, v51
	v_pk_fma_f32 v[2:3], v[54:55], v[58:59], v[2:3]
	ds_read_b128 v[48:51], v63 offset:512
	ds_read_b128 v[52:55], v64 offset:256
	s_waitcnt lgkmcnt(6)
	v_lshlrev_b32_e32 v60, 16, v232
	v_and_b32_e32 v61, 0xffff0000, v232
	v_lshlrev_b32_e32 v56, 16, v233
	v_and_b32_e32 v57, 0xffff0000, v233
	v_fma_f32 v14, v228, v60, v14
	v_fma_f32 v12, v229, v61, v12
	v_fma_f32 v15, v230, v56, v15
	v_fma_f32 v13, v231, v57, v13
	ds_read_b128 v[228:231], v63 offset:528
	s_waitcnt lgkmcnt(6)
	v_lshlrev_b32_e32 v58, 16, v234
	v_and_b32_e32 v59, 0xffff0000, v234
	v_pk_fma_f32 v[0:1], v[236:237], v[58:59], v[0:1]
	v_lshlrev_b32_e32 v60, 16, v235
	v_and_b32_e32 v61, 0xffff0000, v235
	v_pk_fma_f32 v[10:11], v[238:239], v[60:61], v[10:11]
	ds_read_b128 v[232:235], v63 offset:544
	ds_read_b128 v[236:239], v64 offset:272
	s_waitcnt lgkmcnt(6)
	v_lshlrev_b32_e32 v56, 16, v244
	v_and_b32_e32 v57, 0xffff0000, v244
	v_pk_fma_f32 v[8:9], v[240:241], v[56:57], v[8:9]
	v_lshlrev_b32_e32 v58, 16, v245
	v_and_b32_e32 v59, 0xffff0000, v245
	v_pk_fma_f32 v[6:7], v[242:243], v[58:59], v[6:7]
	ds_read_b128 v[240:243], v63 offset:560
	s_waitcnt lgkmcnt(6)
	v_lshlrev_b32_e32 v60, 16, v246
	v_and_b32_e32 v61, 0xffff0000, v246
	v_pk_fma_f32 v[4:5], v[248:249], v[60:61], v[4:5]
	v_lshlrev_b32_e32 v56, 16, v247
	v_and_b32_e32 v57, 0xffff0000, v247
	v_pk_fma_f32 v[2:3], v[250:251], v[56:57], v[2:3]
	ds_read_b128 v[244:247], v63 offset:2048
	ds_read_b128 v[248:251], v64 offset:1040
	s_waitcnt lgkmcnt(6)
	v_lshlrev_b32_e32 v58, 16, v52
	v_and_b32_e32 v59, 0xffff0000, v52
	v_pk_fma_f32 v[26:27], v[48:49], v[58:59], v[26:27]
	v_lshlrev_b32_e32 v60, 16, v53
	v_and_b32_e32 v61, 0xffff0000, v53
	v_pk_fma_f32 v[22:23], v[50:51], v[60:61], v[22:23]
	ds_read_b128 v[48:51], v63 offset:2064
	s_waitcnt lgkmcnt(6)
	v_lshlrev_b32_e32 v56, 16, v54
	v_and_b32_e32 v57, 0xffff0000, v54
	v_pk_fma_f32 v[20:21], v[228:229], v[56:57], v[20:21]
	v_lshlrev_b32_e32 v58, 16, v55
	v_and_b32_e32 v59, 0xffff0000, v55
	v_pk_fma_f32 v[16:17], v[230:231], v[58:59], v[16:17]
	ds_read_b128 v[52:55], v63 offset:2080
	ds_read_b128 v[228:231], v64 offset:1056
	s_waitcnt lgkmcnt(6)
	v_lshlrev_b32_e32 v60, 16, v236
	v_and_b32_e32 v61, 0xffff0000, v236
	v_pk_fma_f32 v[30:31], v[232:233], v[60:61], v[30:31]
	v_lshlrev_b32_e32 v56, 16, v237
	v_and_b32_e32 v57, 0xffff0000, v237
	v_pk_fma_f32 v[28:29], v[234:235], v[56:57], v[28:29]
	ds_read_b128 v[232:235], v63 offset:2096
	s_waitcnt lgkmcnt(6)
	v_lshlrev_b32_e32 v58, 16, v238
	v_and_b32_e32 v59, 0xffff0000, v238
	v_pk_fma_f32 v[24:25], v[240:241], v[58:59], v[24:25]
	v_lshlrev_b32_e32 v60, 16, v239
	v_and_b32_e32 v61, 0xffff0000, v239
	v_pk_fma_f32 v[18:19], v[242:243], v[60:61], v[18:19]
	ds_read_b128 v[236:239], v63 offset:3584
	ds_read_b128 v[240:243], v64 offset:1824
	s_waitcnt lgkmcnt(6)
	v_lshlrev_b32_e32 v56, 16, v248
	v_and_b32_e32 v57, 0xffff0000, v248
	v_pk_fma_f32 v[26:27], v[244:245], v[56:57], v[26:27]
	v_lshlrev_b32_e32 v58, 16, v249
	v_and_b32_e32 v59, 0xffff0000, v249
	v_pk_fma_f32 v[22:23], v[246:247], v[58:59], v[22:23]
	ds_read_b128 v[244:247], v63 offset:3600
	s_waitcnt lgkmcnt(6)
	v_lshlrev_b32_e32 v60, 16, v250
	v_and_b32_e32 v61, 0xffff0000, v250
	v_pk_fma_f32 v[20:21], v[48:49], v[60:61], v[20:21]
	v_lshlrev_b32_e32 v56, 16, v251
	v_and_b32_e32 v57, 0xffff0000, v251
	v_pk_fma_f32 v[16:17], v[50:51], v[56:57], v[16:17]
	ds_read_b128 v[248:251], v63 offset:3616
	ds_read_b128 v[48:51], v64 offset:1840
	s_waitcnt lgkmcnt(6)
	v_lshlrev_b32_e32 v58, 16, v228
	v_and_b32_e32 v59, 0xffff0000, v228
	v_pk_fma_f32 v[30:31], v[52:53], v[58:59], v[30:31]
	v_lshlrev_b32_e32 v60, 16, v229
	v_and_b32_e32 v61, 0xffff0000, v229
	v_pk_fma_f32 v[28:29], v[54:55], v[60:61], v[28:29]
	ds_read_b128 v[52:55], v63 offset:3632
	s_waitcnt lgkmcnt(6)
	v_lshlrev_b32_e32 v56, 16, v230
	v_and_b32_e32 v57, 0xffff0000, v230
	v_pk_fma_f32 v[24:25], v[232:233], v[56:57], v[24:25]
	v_lshlrev_b32_e32 v58, 16, v231
	v_and_b32_e32 v59, 0xffff0000, v231
	v_pk_fma_f32 v[18:19], v[234:235], v[58:59], v[18:19]
	ds_read_b128 v[228:231], v63 offset:5120
	ds_read_b128 v[232:235], v64 offset:2608
	s_waitcnt lgkmcnt(6)
; DI void unpack8(u32x4 v, float* o) { o[0] = lo16(v.x); o[1] = hi16(v.x); o[2] = lo16(v.y); o[3] = hi16(v.y); o[4] = lo16(v.z); o[5] = hi16(v.z); o[6] = lo16(v.w); o[7] = hi16(v.w); }
; DI void gdn_conv16(const bf16_t* raw, const float* cw, int ti, int cch, float* out) {
; #pragma unroll
;     for (int e = 0; e < 16; ++e) out[e] = 0.f;
; #pragma unroll 1
;     for (int j = 0; j < 5; ++j) {
;         const bf16_t* rp = raw + (ti + j) * 392 + cch;
;         float xv[16];
;         unpack8(*(const u32x4*)rp, xv); unpack8(*(const u32x4*)(rp + 8), xv + 8);
;         const float* w = cw + j * 384 + cch;
; #pragma unroll
;         for (int e4 = 0; e4 < 4; ++e4) { const f32x4 wv = *(const f32x4*)(w + 4 * e4);
; #pragma unroll
;             for (int e = 0; e < 4; ++e) out[4 * e4 + e] += wv[e] * xv[4 * e4 + e]; }
;     }
	v_lshlrev_b32_e32 v60, 16, v240
	v_and_b32_e32 v61, 0xffff0000, v240
	v_pk_fma_f32 v[26:27], v[236:237], v[60:61], v[26:27]
	v_lshlrev_b32_e32 v56, 16, v241
	v_and_b32_e32 v57, 0xffff0000, v241
	v_pk_fma_f32 v[22:23], v[238:239], v[56:57], v[22:23]
	ds_read_b128 v[236:239], v63 offset:5136
	s_waitcnt lgkmcnt(6)
	v_lshlrev_b32_e32 v58, 16, v242
	v_and_b32_e32 v59, 0xffff0000, v242
	v_pk_fma_f32 v[20:21], v[244:245], v[58:59], v[20:21]
	v_lshlrev_b32_e32 v60, 16, v243
	v_and_b32_e32 v61, 0xffff0000, v243
	v_pk_fma_f32 v[16:17], v[246:247], v[60:61], v[16:17]
	ds_read_b128 v[240:243], v63 offset:5152
	ds_read_b128 v[244:247], v64 offset:2624
	s_waitcnt lgkmcnt(6)
	v_lshlrev_b32_e32 v56, 16, v48
	v_and_b32_e32 v57, 0xffff0000, v48
	v_pk_fma_f32 v[30:31], v[248:249], v[56:57], v[30:31]
	v_lshlrev_b32_e32 v58, 16, v49
	v_and_b32_e32 v59, 0xffff0000, v49
	v_pk_fma_f32 v[28:29], v[250:251], v[58:59], v[28:29]
	ds_read_b128 v[248:251], v63 offset:5168
	s_waitcnt lgkmcnt(6)
	v_lshlrev_b32_e32 v60, 16, v50
	v_and_b32_e32 v61, 0xffff0000, v50
	v_pk_fma_f32 v[24:25], v[52:53], v[60:61], v[24:25]
	v_lshlrev_b32_e32 v56, 16, v51
	v_and_b32_e32 v57, 0xffff0000, v51
	v_pk_fma_f32 v[18:19], v[54:55], v[56:57], v[18:19]
	ds_read_b128 v[48:51], v63 offset:6656
	ds_read_b128 v[52:55], v64 offset:3392
	s_waitcnt lgkmcnt(6)
	v_lshlrev_b32_e32 v58, 16, v232
	v_and_b32_e32 v59, 0xffff0000, v232
	v_pk_fma_f32 v[26:27], v[228:229], v[58:59], v[26:27]
	v_lshlrev_b32_e32 v60, 16, v233
	v_and_b32_e32 v61, 0xffff0000, v233
	v_pk_fma_f32 v[22:23], v[230:231], v[60:61], v[22:23]
	ds_read_b128 v[228:231], v63 offset:6672
	s_waitcnt lgkmcnt(6)
	v_lshlrev_b32_e32 v56, 16, v234
	v_and_b32_e32 v57, 0xffff0000, v234
	v_pk_fma_f32 v[20:21], v[236:237], v[56:57], v[20:21]
	v_lshlrev_b32_e32 v58, 16, v235
	v_and_b32_e32 v59, 0xffff0000, v235
	v_pk_fma_f32 v[16:17], v[238:239], v[58:59], v[16:17]
	ds_read_b128 v[232:235], v63 offset:6688
	ds_read_b128 v[236:239], v64 offset:3408
	s_waitcnt lgkmcnt(6)
	v_lshlrev_b32_e32 v60, 16, v244
	v_and_b32_e32 v61, 0xffff0000, v244
	v_pk_fma_f32 v[30:31], v[240:241], v[60:61], v[30:31]
	v_lshlrev_b32_e32 v56, 16, v245
	v_and_b32_e32 v57, 0xffff0000, v245
	v_pk_fma_f32 v[28:29], v[242:243], v[56:57], v[28:29]
	ds_read_b128 v[240:243], v63 offset:6704
	s_waitcnt lgkmcnt(6)
	v_lshlrev_b32_e32 v58, 16, v246
	v_and_b32_e32 v59, 0xffff0000, v246
	v_pk_fma_f32 v[24:25], v[248:249], v[58:59], v[24:25]
	v_lshlrev_b32_e32 v60, 16, v247
	v_and_b32_e32 v61, 0xffff0000, v247
	v_pk_fma_f32 v[18:19], v[250:251], v[60:61], v[18:19]
	ds_read_b128 v[244:247], v63 offset:1024
	ds_read_b128 v[248:251], v64 offset:512
	s_waitcnt lgkmcnt(6)
	v_lshlrev_b32_e32 v56, 16, v52
	v_and_b32_e32 v57, 0xffff0000, v52
	v_pk_fma_f32 v[26:27], v[48:49], v[56:57], v[26:27]
	v_lshlrev_b32_e32 v58, 16, v53
	v_and_b32_e32 v59, 0xffff0000, v53
	v_pk_fma_f32 v[22:23], v[50:51], v[58:59], v[22:23]
	ds_read_b128 v[48:51], v63 offset:1040
	s_waitcnt lgkmcnt(6)
	v_lshlrev_b32_e32 v60, 16, v54
	v_and_b32_e32 v61, 0xffff0000, v54
	v_pk_fma_f32 v[20:21], v[228:229], v[60:61], v[20:21]
	v_lshlrev_b32_e32 v56, 16, v55
	v_and_b32_e32 v57, 0xffff0000, v55
	v_pk_fma_f32 v[16:17], v[230:231], v[56:57], v[16:17]
	ds_read_b128 v[52:55], v63 offset:1056
	ds_read_b128 v[228:231], v64 offset:528
	s_waitcnt lgkmcnt(6)
	v_lshlrev_b32_e32 v58, 16, v236
	v_and_b32_e32 v59, 0xffff0000, v236
	v_pk_fma_f32 v[30:31], v[232:233], v[58:59], v[30:31]
	v_lshlrev_b32_e32 v60, 16, v237
	v_and_b32_e32 v61, 0xffff0000, v237
	v_pk_fma_f32 v[28:29], v[234:235], v[60:61], v[28:29]
	ds_read_b128 v[232:235], v63 offset:1072
	s_waitcnt lgkmcnt(6)
	v_lshlrev_b32_e32 v56, 16, v238
	v_and_b32_e32 v57, 0xffff0000, v238
	v_pk_fma_f32 v[24:25], v[240:241], v[56:57], v[24:25]
	v_lshlrev_b32_e32 v58, 16, v239
	v_and_b32_e32 v59, 0xffff0000, v239
	v_pk_fma_f32 v[18:19], v[242:243], v[58:59], v[18:19]
	ds_read_b128 v[236:239], v63 offset:2560
	ds_read_b128 v[240:243], v64 offset:1296
	s_waitcnt lgkmcnt(6)
	v_lshlrev_b32_e32 v60, 16, v248
	v_and_b32_e32 v61, 0xffff0000, v248
	v_pk_fma_f32 v[32:33], v[244:245], v[60:61], v[32:33]
	v_lshlrev_b32_e32 v56, 16, v249
	v_and_b32_e32 v57, 0xffff0000, v249
	v_pk_fma_f32 v[34:35], v[246:247], v[56:57], v[34:35]
	ds_read_b128 v[244:247], v63 offset:2576
	s_waitcnt lgkmcnt(6)
	v_lshlrev_b32_e32 v58, 16, v250
	v_and_b32_e32 v59, 0xffff0000, v250
	v_pk_fma_f32 v[36:37], v[48:49], v[58:59], v[36:37]
	v_lshlrev_b32_e32 v60, 16, v251
	v_and_b32_e32 v61, 0xffff0000, v251
	v_pk_fma_f32 v[38:39], v[50:51], v[60:61], v[38:39]
	ds_read_b128 v[248:251], v63 offset:2592
	ds_read_b128 v[48:51], v64 offset:1312
	s_waitcnt lgkmcnt(6)
	v_lshlrev_b32_e32 v56, 16, v228
	v_and_b32_e32 v57, 0xffff0000, v228
	v_pk_fma_f32 v[40:41], v[52:53], v[56:57], v[40:41]
	v_lshlrev_b32_e32 v58, 16, v229
	v_and_b32_e32 v59, 0xffff0000, v229
	v_pk_fma_f32 v[42:43], v[54:55], v[58:59], v[42:43]
	ds_read_b128 v[52:55], v63 offset:2608
	s_waitcnt lgkmcnt(6)
	v_lshlrev_b32_e32 v60, 16, v230
	v_and_b32_e32 v61, 0xffff0000, v230
	v_pk_fma_f32 v[44:45], v[232:233], v[60:61], v[44:45]
	v_lshlrev_b32_e32 v56, 16, v231
	v_and_b32_e32 v57, 0xffff0000, v231
	v_pk_fma_f32 v[46:47], v[234:235], v[56:57], v[46:47]
	ds_read_b128 v[228:231], v63 offset:4096
	ds_read_b128 v[232:235], v64 offset:2080
	s_waitcnt lgkmcnt(6)
	v_lshlrev_b32_e32 v58, 16, v240
	v_and_b32_e32 v59, 0xffff0000, v240
	v_pk_fma_f32 v[32:33], v[236:237], v[58:59], v[32:33]
	v_lshlrev_b32_e32 v60, 16, v241
	v_and_b32_e32 v61, 0xffff0000, v241
	v_pk_fma_f32 v[34:35], v[238:239], v[60:61], v[34:35]
	ds_read_b128 v[236:239], v63 offset:4112
	s_waitcnt lgkmcnt(6)
; DI void unpack8(u32x4 v, float* o) { o[0] = lo16(v.x); o[1] = hi16(v.x); o[2] = lo16(v.y); o[3] = hi16(v.y); o[4] = lo16(v.z); o[5] = hi16(v.z); o[6] = lo16(v.w); o[7] = hi16(v.w); }
; DI void gdn_conv16(const bf16_t* raw, const float* cw, int ti, int cch, float* out) {
; #pragma unroll
;     for (int e = 0; e < 16; ++e) out[e] = 0.f;
; #pragma unroll 1
;     for (int j = 0; j < 5; ++j) {
;         const bf16_t* rp = raw + (ti + j) * 392 + cch;
;         float xv[16];
;         unpack8(*(const u32x4*)rp, xv); unpack8(*(const u32x4*)(rp + 8), xv + 8);
;         const float* w = cw + j * 384 + cch;
; #pragma unroll
;         for (int e4 = 0; e4 < 4; ++e4) { const f32x4 wv = *(const f32x4*)(w + 4 * e4);
; #pragma unroll
;             for (int e = 0; e < 4; ++e) out[4 * e4 + e] += wv[e] * xv[4 * e4 + e]; }
;     }
	v_lshlrev_b32_e32 v56, 16, v242
	v_and_b32_e32 v57, 0xffff0000, v242
	v_pk_fma_f32 v[36:37], v[244:245], v[56:57], v[36:37]
	v_lshlrev_b32_e32 v58, 16, v243
	v_and_b32_e32 v59, 0xffff0000, v243
	v_pk_fma_f32 v[38:39], v[246:247], v[58:59], v[38:39]
	ds_read_b128 v[240:243], v63 offset:4128
	ds_read_b128 v[244:247], v64 offset:2096
	s_waitcnt lgkmcnt(6)
	v_lshlrev_b32_e32 v60, 16, v48
	v_and_b32_e32 v61, 0xffff0000, v48
	v_pk_fma_f32 v[40:41], v[248:249], v[60:61], v[40:41]
	v_lshlrev_b32_e32 v56, 16, v49
	v_and_b32_e32 v57, 0xffff0000, v49
	v_pk_fma_f32 v[42:43], v[250:251], v[56:57], v[42:43]
	ds_read_b128 v[248:251], v63 offset:4144
	s_waitcnt lgkmcnt(6)
	v_lshlrev_b32_e32 v58, 16, v50
	v_and_b32_e32 v59, 0xffff0000, v50
	v_pk_fma_f32 v[44:45], v[52:53], v[58:59], v[44:45]
	v_lshlrev_b32_e32 v60, 16, v51
	v_and_b32_e32 v61, 0xffff0000, v51
	v_pk_fma_f32 v[46:47], v[54:55], v[60:61], v[46:47]
	ds_read_b128 v[48:51], v63 offset:5632
	ds_read_b128 v[52:55], v64 offset:2864
	s_waitcnt lgkmcnt(6)
	v_lshlrev_b32_e32 v56, 16, v232
	v_and_b32_e32 v57, 0xffff0000, v232
	v_pk_fma_f32 v[32:33], v[228:229], v[56:57], v[32:33]
	v_lshlrev_b32_e32 v58, 16, v233
	v_and_b32_e32 v59, 0xffff0000, v233
	v_pk_fma_f32 v[34:35], v[230:231], v[58:59], v[34:35]
	ds_read_b128 v[228:231], v63 offset:5648
	s_waitcnt lgkmcnt(6)
	v_lshlrev_b32_e32 v60, 16, v234
	v_and_b32_e32 v61, 0xffff0000, v234
	v_pk_fma_f32 v[36:37], v[236:237], v[60:61], v[36:37]
	v_lshlrev_b32_e32 v56, 16, v235
	v_and_b32_e32 v57, 0xffff0000, v235
	v_pk_fma_f32 v[38:39], v[238:239], v[56:57], v[38:39]
	ds_read_b128 v[232:235], v63 offset:5664
	ds_read_b128 v[236:239], v64 offset:2880
	s_waitcnt lgkmcnt(6)
	v_lshlrev_b32_e32 v58, 16, v244
	v_and_b32_e32 v59, 0xffff0000, v244
	v_pk_fma_f32 v[40:41], v[240:241], v[58:59], v[40:41]
	v_lshlrev_b32_e32 v60, 16, v245
	v_and_b32_e32 v61, 0xffff0000, v245
	v_pk_fma_f32 v[42:43], v[242:243], v[60:61], v[42:43]
	ds_read_b128 v[240:243], v63 offset:5680
	s_waitcnt lgkmcnt(6)
	v_lshlrev_b32_e32 v56, 16, v246
	v_and_b32_e32 v57, 0xffff0000, v246
	v_pk_fma_f32 v[44:45], v[248:249], v[56:57], v[44:45]
	v_lshlrev_b32_e32 v58, 16, v247
	v_and_b32_e32 v59, 0xffff0000, v247
	v_pk_fma_f32 v[46:47], v[250:251], v[58:59], v[46:47]
	ds_read_b128 v[244:247], v63 offset:7168
	ds_read_b128 v[248:251], v64 offset:3648
	s_waitcnt lgkmcnt(6)
	v_lshlrev_b32_e32 v60, 16, v52
	v_and_b32_e32 v61, 0xffff0000, v52
	v_pk_fma_f32 v[32:33], v[48:49], v[60:61], v[32:33]
	v_lshlrev_b32_e32 v56, 16, v53
	v_and_b32_e32 v57, 0xffff0000, v53
	v_pk_fma_f32 v[34:35], v[50:51], v[56:57], v[34:35]
	ds_read_b128 v[48:51], v63 offset:7184
	s_waitcnt lgkmcnt(6)
	v_lshlrev_b32_e32 v58, 16, v54
	v_and_b32_e32 v59, 0xffff0000, v54
	v_pk_fma_f32 v[36:37], v[228:229], v[58:59], v[36:37]
	v_lshlrev_b32_e32 v60, 16, v55
	v_and_b32_e32 v61, 0xffff0000, v55
	v_pk_fma_f32 v[38:39], v[230:231], v[60:61], v[38:39]
	ds_read_b128 v[52:55], v63 offset:7200
	ds_read_b128 v[228:231], v64 offset:3664
	s_waitcnt lgkmcnt(6)
	v_lshlrev_b32_e32 v56, 16, v236
	v_and_b32_e32 v57, 0xffff0000, v236
	v_pk_fma_f32 v[40:41], v[232:233], v[56:57], v[40:41]
	v_lshlrev_b32_e32 v58, 16, v237
	v_and_b32_e32 v59, 0xffff0000, v237
	v_pk_fma_f32 v[42:43], v[234:235], v[58:59], v[42:43]
	ds_read_b128 v[232:235], v63 offset:7216
	s_waitcnt lgkmcnt(6)
	v_lshlrev_b32_e32 v60, 16, v238
	v_and_b32_e32 v61, 0xffff0000, v238
	v_pk_fma_f32 v[44:45], v[240:241], v[60:61], v[44:45]
	v_lshlrev_b32_e32 v56, 16, v239
	v_and_b32_e32 v57, 0xffff0000, v239
	v_pk_fma_f32 v[46:47], v[242:243], v[56:57], v[46:47]
	s_waitcnt lgkmcnt(4)
	v_lshlrev_b32_e32 v58, 16, v248
	v_and_b32_e32 v59, 0xffff0000, v248
	v_pk_fma_f32 v[32:33], v[244:245], v[58:59], v[32:33]
	v_lshlrev_b32_e32 v60, 16, v249
	v_and_b32_e32 v61, 0xffff0000, v249
	v_pk_fma_f32 v[34:35], v[246:247], v[60:61], v[34:35]
	s_waitcnt lgkmcnt(3)
	v_lshlrev_b32_e32 v56, 16, v250
	v_and_b32_e32 v57, 0xffff0000, v250
	v_pk_fma_f32 v[36:37], v[48:49], v[56:57], v[36:37]
	v_lshlrev_b32_e32 v58, 16, v251
	v_and_b32_e32 v59, 0xffff0000, v251
	v_pk_fma_f32 v[38:39], v[50:51], v[58:59], v[38:39]
	s_waitcnt lgkmcnt(1)
	v_lshlrev_b32_e32 v60, 16, v228
	v_and_b32_e32 v61, 0xffff0000, v228
	v_pk_fma_f32 v[40:41], v[52:53], v[60:61], v[40:41]
	v_lshlrev_b32_e32 v56, 16, v229
	v_and_b32_e32 v57, 0xffff0000, v229
	v_pk_fma_f32 v[42:43], v[54:55], v[56:57], v[42:43]
	s_waitcnt lgkmcnt(0)
; DI float siluf(float x) { return x * __builtin_amdgcn_rcpf(1.f + __expf(-x)); }
; DI void gdn_conv16(const bf16_t* raw, const float* cw, int ti, int cch, float* out) {
;     ...
;     for (int e = 0; e < 16; ++e) out[e] = siluf(out[e]);
	v_lshlrev_b32_e32 v58, 16, v230
	v_and_b32_e32 v59, 0xffff0000, v230
	v_pk_fma_f32 v[44:45], v[232:233], v[58:59], v[44:45]
	v_lshlrev_b32_e32 v60, 16, v231
	v_and_b32_e32 v61, 0xffff0000, v231
	v_pk_fma_f32 v[46:47], v[234:235], v[60:61], v[46:47]
	s_mov_b32 s0, 0
	v_mul_f32_e32 v52, 0xbfb8aa3b, v8
	v_exp_f32_e32 v52, v52
	v_mul_f32_e32 v53, 0xbfb8aa3b, v6
	v_exp_f32_e32 v53, v53
	v_mul_f32_e32 v50, 0xbfb8aa3b, v0
	v_add_f32_e32 v52, 1.0, v52
	v_mul_f32_e32 v48, 0xbfb8aa3b, v14
	v_mul_f32_e32 v49, 0xbfb8aa3b, v15
	v_exp_f32_e32 v50, v50
	v_mul_f32_e32 v51, 0xbfb8aa3b, v10
	v_rcp_f32_e32 v54, v52
	v_add_f32_e32 v52, 1.0, v53
	v_mul_f32_e32 v53, 0xbfb8aa3b, v4
	v_exp_f32_e32 v48, v48
	v_exp_f32_e32 v49, v49
	v_exp_f32_e32 v51, v51
	v_exp_f32_e32 v53, v53
	v_add_f32_e32 v50, 1.0, v50
	v_mul_f32_e32 v55, 0xbfb8aa3b, v2
	v_add_f32_e32 v48, 1.0, v48
	v_add_f32_e32 v49, 1.0, v49
	v_rcp_f32_e32 v50, v50
	v_add_f32_e32 v51, 1.0, v51
	v_exp_f32_e32 v55, v55
	v_rcp_f32_e32 v57, v52
	v_add_f32_e32 v52, 1.0, v53
	v_rcp_f32_e32 v48, v48
	v_rcp_f32_e32 v49, v49
	v_rcp_f32_e32 v51, v51
	v_rcp_f32_e32 v58, v52
	v_add_f32_e32 v52, 1.0, v55
	v_mul_f32_e32 v56, v0, v50
	v_mul_f32_e32 v0, 0xbfb8aa3b, v26
	v_rcp_f32_e32 v55, v52
	v_pk_mul_f32 v[52:53], v[14:15], v[48:49]
	v_mul_f32_e32 v15, v10, v51
	v_mul_f32_e32 v10, v8, v54
	v_mul_f32_e32 v8, v6, v57
	v_mul_f32_e32 v6, v4, v58
	v_exp_f32_e32 v0, v0
	v_mul_f32_e32 v4, 0xbfb8aa3b, v27
	v_exp_f32_e32 v14, v4
	v_mul_f32_e32 v4, v2, v55
	v_add_f32_e32 v0, 1.0, v0
	v_mul_f32_e32 v2, 0xbfb8aa3b, v22
	v_rcp_f32_e32 v50, v0
	v_add_f32_e32 v0, 1.0, v14
	v_exp_f32_e32 v2, v2
	v_mul_f32_e32 v14, 0xbfb8aa3b, v23
	v_exp_f32_e32 v14, v14
	v_rcp_f32_e32 v51, v0
	v_add_f32_e32 v0, 1.0, v2
	v_mul_f32_e32 v2, 0xbfb8aa3b, v20
	v_rcp_f32_e32 v54, v0
	v_add_f32_e32 v0, 1.0, v14
	v_exp_f32_e32 v2, v2
	v_mul_f32_e32 v14, 0xbfb8aa3b, v21
	v_exp_f32_e32 v14, v14
	v_rcp_f32_e32 v55, v0
	v_add_f32_e32 v0, 1.0, v2
	v_mul_f32_e32 v2, 0xbfb8aa3b, v16
	v_rcp_f32_e32 v58, v0
	v_add_f32_e32 v0, 1.0, v14
	v_exp_f32_e32 v2, v2
	v_mul_f32_e32 v14, 0xbfb8aa3b, v17
	v_exp_f32_e32 v14, v14
	v_rcp_f32_e32 v59, v0
	v_add_f32_e32 v0, 1.0, v2
	v_mul_f32_e32 v2, 0xbfb8aa3b, v30
	v_rcp_f32_e32 v60, v0
	v_add_f32_e32 v0, 1.0, v14
	v_exp_f32_e32 v2, v2
	v_mul_f32_e32 v14, 0xbfb8aa3b, v31
	v_exp_f32_e32 v14, v14
	v_rcp_f32_e32 v61, v0
	v_add_f32_e32 v0, 1.0, v2
	v_mul_f32_e32 v2, 0xbfb8aa3b, v28
	v_rcp_f32_e32 v62, v0
	v_add_f32_e32 v0, 1.0, v14
	v_exp_f32_e32 v2, v2
	v_mul_f32_e32 v14, 0xbfb8aa3b, v29
	v_exp_f32_e32 v14, v14
	v_rcp_f32_e32 v63, v0
	v_add_f32_e32 v0, 1.0, v2
	v_mul_f32_e32 v2, 0xbfb8aa3b, v24
	v_rcp_f32_e32 v64, v0
	v_add_f32_e32 v0, 1.0, v14
	v_exp_f32_e32 v2, v2
	v_mul_f32_e32 v14, 0xbfb8aa3b, v25
	v_exp_f32_e32 v14, v14
	v_rcp_f32_e32 v65, v0
	v_add_f32_e32 v0, 1.0, v2
	v_mul_f32_e32 v2, 0xbfb8aa3b, v18
	v_rcp_f32_e32 v66, v0
	v_add_f32_e32 v0, 1.0, v14
	v_exp_f32_e32 v2, v2
	v_mul_f32_e32 v14, 0xbfb8aa3b, v19
	v_exp_f32_e32 v14, v14
	v_rcp_f32_e32 v67, v0
	v_add_f32_e32 v0, 1.0, v2
	v_rcp_f32_e32 v68, v0
	v_add_f32_e32 v0, 1.0, v14
	v_mul_f32_e32 v2, 0xbfb8aa3b, v12
	v_mul_f32_e32 v14, 0xbfb8aa3b, v13
	v_exp_f32_e32 v2, v2
	v_exp_f32_e32 v14, v14
	v_rcp_f32_e32 v69, v0
	v_mul_f32_e32 v48, 0xbfb8aa3b, v11
	v_add_f32_e32 v0, 1.0, v2
	v_add_f32_e32 v2, 1.0, v14
	v_mul_f32_e32 v14, 0xbfb8aa3b, v1
	v_exp_f32_e32 v14, v14
	v_exp_f32_e32 v48, v48
	v_mul_f32_e32 v49, 0xbfb8aa3b, v7
	v_exp_f32_e32 v49, v49
	v_mul_f32_e32 v57, 0xbfb8aa3b, v5
	v_exp_f32_e32 v57, v57
	v_mul_f32_e32 v70, 0xbfb8aa3b, v3
	v_add_f32_e32 v14, 1.0, v14
	v_exp_f32_e32 v70, v70
	v_rcp_f32_e32 v0, v0
	v_rcp_f32_e32 v71, v14
	v_add_f32_e32 v14, 1.0, v48
	v_rcp_f32_e32 v14, v14
	v_add_f32_e32 v49, 1.0, v49
	v_rcp_f32_e32 v72, v49
	v_add_f32_e32 v49, 1.0, v57
	v_rcp_f32_e32 v73, v49
	v_add_f32_e32 v49, 1.0, v70
	v_rcp_f32_e32 v70, v49
	v_mul_f32_e32 v49, v12, v0
	v_mul_f32_e32 v0, 0xbfb8aa3b, v32
	v_mul_f32_e32 v11, v11, v14
	v_exp_f32_e32 v0, v0
	v_mul_f32_e32 v14, 0xbfb8aa3b, v33
	v_exp_f32_e32 v14, v14
	v_pk_mul_f32 v[54:55], v[22:23], v[54:55]
	v_add_f32_e32 v0, 1.0, v0
	v_pk_mul_f32 v[22:23], v[16:17], v[60:61]
	v_pk_mul_f32 v[16:17], v[18:19], v[68:69]
	v_rcp_f32_e32 v18, v0
	v_add_f32_e32 v0, 1.0, v14
	v_rcp_f32_e32 v19, v0
	v_mul_f32_e32 v0, 0xbfb8aa3b, v34
	v_exp_f32_e32 v0, v0
	v_mul_f32_e32 v14, 0xbfb8aa3b, v35
	v_exp_f32_e32 v14, v14
	v_pk_mul_f32 v[32:33], v[32:33], v[18:19]
	v_add_f32_e32 v0, 1.0, v0
	v_rcp_f32_e32 v18, v0
	v_add_f32_e32 v0, 1.0, v14
	v_rcp_f32_e32 v19, v0
	v_mul_f32_e32 v0, 0xbfb8aa3b, v36
	v_exp_f32_e32 v0, v0
	v_mul_f32_e32 v14, 0xbfb8aa3b, v37
	v_exp_f32_e32 v14, v14
	v_pk_mul_f32 v[34:35], v[34:35], v[18:19]
	v_add_f32_e32 v0, 1.0, v0
	v_rcp_f32_e32 v18, v0
	v_add_f32_e32 v0, 1.0, v14
	v_rcp_f32_e32 v19, v0
	v_mul_f32_e32 v0, 0xbfb8aa3b, v38
	v_exp_f32_e32 v0, v0
	v_mul_f32_e32 v14, 0xbfb8aa3b, v39
	v_exp_f32_e32 v14, v14
	v_pk_mul_f32 v[36:37], v[36:37], v[18:19]
	v_add_f32_e32 v0, 1.0, v0
	v_rcp_f32_e32 v18, v0
	v_add_f32_e32 v0, 1.0, v14
	v_rcp_f32_e32 v19, v0
	v_mul_f32_e32 v0, 0xbfb8aa3b, v40
	v_exp_f32_e32 v0, v0
	v_mul_f32_e32 v14, 0xbfb8aa3b, v41
	v_exp_f32_e32 v14, v14
	v_pk_mul_f32 v[38:39], v[38:39], v[18:19]
	v_add_f32_e32 v0, 1.0, v0
	v_rcp_f32_e32 v18, v0
	v_add_f32_e32 v0, 1.0, v14
	v_rcp_f32_e32 v19, v0
	v_mul_f32_e32 v0, 0xbfb8aa3b, v42
	v_exp_f32_e32 v0, v0
	v_mul_f32_e32 v14, 0xbfb8aa3b, v43
	v_exp_f32_e32 v14, v14
	v_rcp_f32_e32 v2, v2
	v_add_f32_e32 v0, 1.0, v0
	v_pk_mul_f32 v[40:41], v[40:41], v[18:19]
	v_rcp_f32_e32 v18, v0
	v_add_f32_e32 v0, 1.0, v14
	v_mul_f32_e32 v14, 0xbfb8aa3b, v44
	v_exp_f32_e32 v14, v14
; DI void gdn_prep_item(const P& p, int l, int item, unsigned char* smem) {
;     ...
;     float sq_ = 0.f, sk_ = 0.f;
; #pragma unroll
;     for (int e = 0; e < 16; ++e) { sq_ += xq[e] * xq[e]; sk_ += xk[e] * xk[e]; }
;     sq_ += __shfl_xor(sq_, 1); sq_ += __shfl_xor(sq_, 2); sq_ += __shfl_xor(sq_, 4);
;     sk_ += __shfl_xor(sk_, 1); sk_ += __shfl_xor(sk_, 2); sk_ += __shfl_xor(sk_, 4);
;     const float rq = rsqrtf(sq_ + 1e-6f) * 0.08838834764831845f, rk = rsqrtf(sk_ + 1e-6f);
; #pragma unroll
;     for (int e = 0; e < 16; ++e) { xq[e] *= rq; xk[e] *= rk; }
	v_mul_f32_e32 v19, 0xbfb8aa3b, v45
	v_mul_f32_e32 v57, v13, v2
	v_mul_f32_e32 v76, v3, v70
	v_pk_mul_f32 v[2:3], v[24:25], v[66:67]
	v_exp_f32_e32 v25, v19
	v_rcp_f32_e32 v19, v0
	v_add_f32_e32 v0, 1.0, v14
	v_mul_f32_e32 v14, 0xbfb8aa3b, v46
	v_rcp_f32_e32 v24, v0
	v_add_f32_e32 v0, 1.0, v25
	v_exp_f32_e32 v14, v14
	v_mul_f32_e32 v25, 0xbfb8aa3b, v47
	v_pk_mul_f32 v[12:13], v[28:29], v[64:65]
	v_exp_f32_e32 v29, v25
	v_rcp_f32_e32 v25, v0
	v_add_f32_e32 v0, 1.0, v14
	v_pk_mul_f32 v[50:51], v[26:27], v[50:51]
	v_rcp_f32_e32 v28, v0
	v_add_f32_e32 v0, 1.0, v29
	v_mul_f32_e32 v48, 0xbfb8aa3b, v9
	v_pk_mul_f32 v[26:27], v[20:21], v[58:59]
	v_pk_mul_f32 v[20:21], v[30:31], v[62:63]
	v_rcp_f32_e32 v29, v0
	v_pk_mul_f32 v[30:31], v[52:53], v[52:53]
	v_mul_f32_e32 v0, v51, v51
	v_exp_f32_e32 v48, v48
	v_fma_f32 v14, v49, v49, v30
	v_pk_fma_f32 v[58:59], v[50:51], v[50:51], v[0:1] op_sel_hi:[1,1,0]
	v_add_f32_e32 v14, v31, v14
	v_pk_fma_f32 v[30:31], v[54:55], v[54:55], v[58:59]
	v_mul_f32_e32 v0, v55, v55
	v_pk_mul_f32 v[58:59], v[56:57], v[56:57]
	v_pk_add_f32 v[30:31], v[0:1], v[30:31] op_sel_hi:[0,1]
	v_add_f32_e32 v0, v59, v14
	v_add_f32_e32 v59, v58, v0
	v_mov_b32_e32 v0, v26
	v_mov_b32_e32 v70, v26
	v_add_f32_e32 v48, 1.0, v48
	v_pk_mul_f32 v[66:67], v[0:1], v[70:71]
	v_rcp_f32_e32 v48, v48
	v_pk_fma_f32 v[0:1], v[0:1], v[70:71], v[30:31]
	v_pk_mul_f32 v[30:31], v[66:67], v[66:67]
	v_mul_f32_e32 v58, v27, v27
	v_mov_b32_e32 v1, v31
	v_pk_mul_f32 v[60:61], v[22:23], v[22:23]
	v_pk_mul_f32 v[62:63], v[10:11], v[10:11]
	v_pk_add_f32 v[0:1], v[0:1], v[58:59]
	v_mov_b32_e32 v14, v22
	v_pk_mul_f32 v[64:65], v[20:21], v[20:21]
	v_pk_fma_f32 v[0:1], v[14:15], v[14:15], v[0:1]
	v_mov_b32_e32 v30, v61
	v_mov_b32_e32 v31, v63
	v_mul_f32_e32 v9, v9, v48
	v_pk_add_f32 v[0:1], v[30:31], v[0:1]
	v_mov_b32_e32 v30, v64
	v_mov_b32_e32 v31, v62
	v_pk_add_f32 v[0:1], v[30:31], v[0:1]
	v_pk_mul_f32 v[30:31], v[8:9], v[8:9]
	v_mul_f32_e32 v7, v7, v72
	v_pk_mul_f32 v[58:59], v[12:13], v[12:13]
	v_mov_b32_e32 v64, v65
	v_mov_b32_e32 v65, v31
	v_pk_mul_f32 v[60:61], v[6:7], v[6:7]
	v_pk_add_f32 v[0:1], v[64:65], v[0:1]
	v_mov_b32_e32 v64, v58
	v_mov_b32_e32 v65, v30
	v_mul_f32_e32 v5, v5, v73
	v_pk_mul_f32 v[62:63], v[2:3], v[2:3]
	v_pk_add_f32 v[0:1], v[64:65], v[0:1]
	v_mov_b32_e32 v30, v59
	v_mov_b32_e32 v31, v61
	v_pk_mul_f32 v[68:69], v[4:5], v[4:5]
	v_and_b32_e32 v86, 64, v177
	v_pk_add_f32 v[0:1], v[30:31], v[0:1]
	v_mov_b32_e32 v30, v62
	v_mov_b32_e32 v31, v60
	v_pk_mul_f32 v[72:73], v[16:17], v[16:17]
	v_xor_b32_e32 v14, 1, v177
	v_add_u32_e32 v48, 64, v86
	v_pk_add_f32 v[0:1], v[30:31], v[0:1]
	v_mov_b32_e32 v30, v63
	v_mov_b32_e32 v31, v69
	v_cmp_lt_i32_e32 vcc, v14, v48
	v_pk_add_f32 v[0:1], v[30:31], v[0:1]
	v_mov_b32_e32 v30, v72
	v_mov_b32_e32 v31, v68
	v_mul_f32_e32 v71, v76, v76
	v_cndmask_b32_e32 v14, v177, v14, vcc
	v_pk_add_f32 v[0:1], v[30:31], v[0:1]
	v_mov_b32_e32 v70, v73
	v_lshlrev_b32_e32 v14, 2, v14
	v_pk_add_f32 v[0:1], v[70:71], v[0:1]
	ds_bpermute_b32 v31, v14, v1
	ds_bpermute_b32 v30, v14, v0
	v_xor_b32_e32 v14, 2, v177
	v_cmp_lt_i32_e32 vcc, v14, v48
	s_add_i32 s37, s26, 0xcc00
	s_add_i32 s46, s26, 0x11000
	v_cndmask_b32_e32 v14, v177, v14, vcc
	v_lshlrev_b32_e32 v14, 2, v14
	s_waitcnt lgkmcnt(0)
	v_pk_add_f32 v[0:1], v[0:1], v[30:31]
	ds_bpermute_b32 v31, v14, v1
	ds_bpermute_b32 v30, v14, v0
	v_xor_b32_e32 v14, 4, v177
	v_cmp_lt_i32_e32 vcc, v14, v48
	s_add_i32 s3, s26, 0x15400
	s_add_i32 s36, s26, 0x19800
	v_cndmask_b32_e32 v14, v177, v14, vcc
	v_lshlrev_b32_e32 v14, 2, v14
	s_waitcnt lgkmcnt(0)
	v_pk_add_f32 v[0:1], v[0:1], v[30:31]
	ds_bpermute_b32 v31, v14, v1
	ds_bpermute_b32 v30, v14, v0
	s_add_i32 s2, s26, 0x1bc00
	s_add_i32 s28, s26, 0x1c800
	s_add_i32 s44, s26, 0x1c900
	s_add_i32 s45, s26, 0x1ca00
	s_waitcnt lgkmcnt(0)
	v_pk_add_f32 v[0:1], v[0:1], v[30:31]
	s_add_u32 s24, s42, 0x17e4c000
	v_pk_add_f32 v[0:1], v[0:1], s[78:79] op_sel_hi:[1,0]
	v_pk_mul_f32 v[42:43], v[42:43], v[18:19]
	v_mul_f32_e32 v14, 0x4b800000, v1
	v_cmp_gt_f32_e32 vcc, s23, v1
	v_cmp_gt_f32_e64 s[0:1], s23, v0
	v_mov_b32_e32 v18, v53
	v_cndmask_b32_e32 v1, v1, v14, vcc
	v_rsq_f32_e32 v1, v1
	v_mul_f32_e32 v14, 0x4b800000, v0
	v_cndmask_b32_e64 v0, v0, v14, s[0:1]
	v_rsq_f32_e32 v14, v0
	v_mul_f32_e32 v0, 0x45800000, v1
	v_cndmask_b32_e32 v0, v1, v0, vcc
	v_mul_f32_e32 v0, 0x3db504f3, v0
	v_mul_f32_e32 v1, 0x45800000, v14
	v_mov_b32_e32 v19, v57
	v_lshlrev_b32_e32 v132, 5, v80
	s_addc_u32 s22, s43, 0
	v_cndmask_b32_e64 v14, v14, v1, s[0:1]
	v_mov_b32_e32 v48, v52
	v_pk_mul_f32 v[52:53], v[18:19], v[0:1] op_sel_hi:[1,0]
	v_mov_b32_e32 v19, v11
	v_mov_b32_e32 v11, v9
	v_mov_b32_e32 v9, v7
	s_ashr_i32 s6, s27, 3
	v_pk_mul_f32 v[68:69], v[8:9], v[0:1] op_sel_hi:[1,0]
	v_pk_mul_f32 v[78:79], v[16:17], v[14:15] op_sel_hi:[1,0]
	v_lshl_add_u64 v[8:9], s[42:43], 0, v[132:133]
	s_mov_b64 s[40:41], 0x1514c000
	v_bfi_b32 v16, -16, s6, v88
	v_cmp_eq_u32_e64 s[0:1], 0, v80
	v_lshl_add_u64 v[80:81], v[8:9], 0, s[40:41]
	s_mov_b64 s[40:41], 0x1634c000
	v_ashrrev_i32_e32 v17, 31, v16
	v_bfe_u32 v90, v88, 4, 2
	v_mov_b32_e32 v18, v15
	v_lshl_add_u64 v[82:83], v[8:9], 0, s[40:41]
	v_lshlrev_b64 v[8:9], 7, v[16:17]
	v_add_u32_e32 v101, s26, v132
	s_add_i32 s96, s26, 0x1cafc
	s_ashr_i32 s47, s27, 6
	v_pk_mul_f32 v[60:61], v[18:19], v[0:1] op_sel_hi:[1,0]
	v_lshl_add_u32 v19, v90, 4, s26
	v_lshl_add_u64 v[8:9], s[42:43], 0, v[8:9]
	s_mov_b64 s[26:27], 0x1754c000
	v_lshl_add_u64 v[84:85], v[8:9], 0, s[26:27]
	v_lshlrev_b32_e32 v8, 2, v88
	v_add_u32_e32 v113, s28, v8
	v_add_u32_e32 v115, s45, v8
	v_add_u32_e32 v8, -1, v177
	v_cmp_lt_i32_e32 vcc, v8, v86
; DI u32x4 pack8(const float* o) { u32x4 r; r.x = pk2(o[0], o[1]); r.y = pk2(o[2], o[3]); r.z = pk2(o[4], o[5]); r.w = pk2(o[6], o[7]); return r; }
; DI void gdn_prep_item(const P& p, int l, int item, unsigned char* smem) {
;     ...
;     for (int e = 0; e < 16; ++e) { xq[e] *= rq; xk[e] *= rk; }
; #pragma unroll 1
;   for (int dir = 0; dir < 2; ++dir) {
;     const int seq = (dir * 4 + b) * 4 + h;
;     const int c = coff + (dir ? nseg - 1 - cseg : cseg);
;     const int i = dir ? 63 - ti : ti;
;     const int pp = 64 * c + i;
;     if (sub == 0) {
;         const float a_in = dir ? a_raw1 : a_raw0, b_in = dir ? b_raw1 : b_raw0;
;         const float A = __expf(p.gdn_alog[(l * 2 + dir) * 4 + h]);
;         const float xx = a_in + p.gdn_dtb[(l * 2 + dir) * 4 + h];
;         const float sp = fmaxf(xx, 0.f) + log1pf(__expf(-fabsf(xx)));
;         sg[i] = -A * sp; sbeta[i] = __builtin_amdgcn_rcpf(1.f + __expf(-b_in));
;     }
;     __syncthreads();
;     if (tid < 64) {
;         float v = sg[tid];
; #pragma unroll
;         for (int o = 1; o < 64; o <<= 1) { const float u = __shfl_up(v, o); if (tid >= o) v += u; }
;         scum[tid] = v;
;     }
;     __syncthreads();
;     const float cumi = scum[i], cl = scum[63], bet = sbeta[i], ei = __expf(cumi), eo = __expf(cl - cumi);
;     {
;         float t1[16], t2[16];
;         *(u32x4*)(sK + i * 136 + 16 * sub) = pack8(xk); *(u32x4*)(sK + i * 136 + 16 * sub + 8) = pack8(xk + 8);
;         *(u32x4*)(sQ + i * 136 + 16 * sub) = pack8(xq); *(u32x4*)(sQ + i * 136 + 16 * sub + 8) = pack8(xq + 8);
;     ...
;             for (int r = 0; r < 4; ++r) {
;                 const float dcy = __expf(fminf(ci - cj[r], 0.f));
;                 lv[r] = (j0 + r < ii) ? aL[r] * dcy : 0.f;
;                 av[r] = (j0 + r <= ii) ? aA[r] * dcy : 0.f;
;             }
;             *(f32x4*)(sL + ii * LS + j0) = lv;
;             { u32x2 lb; lb.x = pk2(lv[0], lv[1]); lb.y = pk2(lv[2], lv[3]); *(u32x2*)(sLb + ii * 72 + j0) = lb; }
;             { u32x2 ab; ab.x = pk2(av[0], av[1]); ab.y = pk2(av[2], av[3]); *(u32x2*)(AT + (((size_t)seq * 36 + c) * 64 + ii) * 64 + j0) = ab; }
;         }
;     }
;     __syncthreads();
;     if (tid < 64) {
;         const int I = tid >> 4, cc = tid & 15;
;         float tt[16];
; #pragma unroll
;         for (int r = 0; r < 16; ++r) tt[r] = (r == cc) ? 1.f : 0.f;
	v_and_b32_e32 v98, 15, v88
	s_lshl_b32 s4, s47, 5
	v_cndmask_b32_e32 v8, v8, v177, vcc
	v_lshlrev_b32_e32 v117, 2, v8
	v_add_u32_e32 v8, -2, v177
	v_cmp_lt_i32_e32 vcc, v8, v86
	s_sub_i32 s84, s38, s87
	s_and_b32 s5, s4, 32
	v_cndmask_b32_e32 v8, v8, v177, vcc
	v_lshlrev_b32_e32 v119, 2, v8
	v_add_u32_e32 v8, -4, v177
	v_cmp_lt_i32_e32 vcc, v8, v86
	v_mov_b32_e32 v57, v67
	v_pk_mul_f32 v[66:67], v[20:21], v[14:15] op_sel_hi:[1,0]
	v_cndmask_b32_e32 v8, v8, v177, vcc
	v_lshlrev_b32_e32 v121, 2, v8
	v_add_u32_e32 v8, -8, v177
	v_cmp_lt_i32_e32 vcc, v8, v86
	v_lshlrev_b32_e32 v21, 2, v90
	s_cmp_lt_i32 s47, 4
	v_cndmask_b32_e32 v8, v8, v177, vcc
	v_lshlrev_b32_e32 v126, 2, v8
	v_add_u32_e32 v8, -16, v177
	v_cmp_lt_i32_e32 vcc, v8, v86
	s_mov_b32 s7, 0x12d4c000
	v_or_b32_e32 v18, s5, v98
	v_cndmask_b32_e32 v8, v8, v177, vcc
	v_lshlrev_b32_e32 v127, 2, v8
	v_subrev_u32_e32 v8, 32, v177
	v_cmp_lt_i32_e32 vcc, v8, v86
	v_pk_mul_f32 v[44:45], v[44:45], v[24:25]
	s_movk_i32 s8, 0x110
	v_cndmask_b32_e32 v8, v8, v177, vcc
	v_cmp_eq_u32_e32 vcc, 0, v98
	s_movk_i32 s6, 0x90
	s_cselect_b32 s7, s7, 0x13f4c000
	v_cndmask_b32_e64 v147, 0, 1.0, vcc
	v_cmp_eq_u32_e32 vcc, 15, v98
	v_mul_u32_u24_e32 v25, 0x110, v18
	v_or_b32_e32 v18, s5, v21
	v_cndmask_b32_e64 v148, 0, 1.0, vcc
	v_cmp_eq_u32_e32 vcc, 14, v98
	v_pk_mul_f32 v[58:59], v[26:27], v[14:15] op_sel_hi:[1,0]
	v_pk_mul_f32 v[62:63], v[22:23], v[14:15] op_sel_hi:[1,0]
	v_cndmask_b32_e64 v149, 0, 1.0, vcc
	v_cmp_eq_u32_e32 vcc, 13, v98
	v_mul_lo_u32 v20, v16, s8
	v_mul_lo_u32 v22, v16, s6
	v_cndmask_b32_e64 v150, 0, 1.0, vcc
	v_cmp_eq_u32_e32 vcc, 12, v98
	s_cselect_b32 s6, s37, s46
	s_add_u32 s85, s42, s7
	v_lshlrev_b32_e32 v26, 2, v18
	v_cndmask_b32_e64 v151, 0, 1.0, vcc
	v_cmp_eq_u32_e32 vcc, 11, v98
	v_add_u32_e32 v107, v19, v20
	s_addc_u32 s86, s43, 0
	v_or_b32_e32 v27, 2, v18
	v_add3_u32 v144, s3, v20, v26
	v_lshlrev_b32_e32 v20, 1, v18
	s_or_b32 s5, s5, 16
	v_cndmask_b32_e64 v152, 0, 1.0, vcc
	v_cmp_eq_u32_e32 vcc, 10, v98
	v_cmp_lt_i32_e64 s[58:59], v27, v16
	v_cmp_gt_i32_e64 s[62:63], v27, v16
	v_or_b32_e32 v27, 3, v18
	v_add3_u32 v145, s36, v22, v20
	v_or_b32_e32 v22, s5, v21
	v_cndmask_b32_e64 v153, 0, 1.0, vcc
	v_cmp_eq_u32_e32 vcc, 9, v98
	v_pk_mul_f32 v[46:47], v[46:47], v[28:29]
	v_pk_mul_f32 v[64:65], v[10:11], v[0:1] op_sel_hi:[1,0]
	v_lshlrev_b32_e32 v10, 3, v90
	v_and_b32_e32 v24, -16, v88
	v_add_u32_e32 v143, s45, v26
	v_or_b32_e32 v28, 1, v18
	v_cmp_lt_i32_e64 s[64:65], v27, v16
	v_cmp_gt_i32_e64 s[66:67], v27, v16
	v_lshl_add_u32 v146, v22, 2, s45
	v_cmp_lt_i32_e64 s[68:69], v22, v16
	v_cmp_gt_i32_e64 s[70:71], v22, v16
	v_or_b32_e32 v26, 2, v22
	v_or_b32_e32 v27, 1, v22
	v_or_b32_e32 v22, 3, v22
	v_cndmask_b32_e64 v154, 0, 1.0, vcc
	v_cmp_eq_u32_e32 vcc, 8, v98
	v_lshl_add_u32 v109, v16, 2, s45
	v_add_u32_e32 v17, s2, v10
	v_cmp_lt_i32_e64 s[54:55], v18, v16
	v_cmp_gt_i32_e64 s[56:57], v18, v16
	v_cmp_lt_i32_e64 s[60:61], v28, v16
	v_cmp_lt_i32_e64 s[72:73], v26, v16
	v_cmp_lt_i32_e64 s[74:75], v27, v16
	v_cmp_gt_i32_e64 s[76:77], v26, v16
	v_cmp_lt_i32_e64 s[78:79], v22, v16
	v_cmp_gt_i32_e64 s[80:81], v22, v16
	v_cndmask_b32_e64 v155, 0, 1.0, vcc
	v_cmp_eq_u32_e32 vcc, 7, v98
	v_lshl_add_u32 v16, v24, 2, s3
	v_or_b32_e32 v22, 15, v88
	v_cmp_gt_i32_e64 s[38:39], 64, v88
	v_add_u32_e32 v105, s46, v132
	v_cmp_eq_u32_e64 s[40:41], 0, v88
	v_add_u32_e32 v23, s36, v10
	v_cmp_gt_i32_e64 s[42:43], 1, v88
	v_cmp_gt_i32_e64 s[26:27], 2, v88
	v_cmp_gt_i32_e64 s[46:47], 4, v88
	v_cmp_gt_i32_e64 s[48:49], 8, v88
	v_cmp_gt_i32_e64 s[50:51], 16, v88
	v_cmp_gt_i32_e64 s[52:53], 32, v88
	v_cndmask_b32_e64 v156, 0, 1.0, vcc
	v_cmp_eq_u32_e32 vcc, 6, v98
	v_mad_u64_u32 v[86:87], s[36:37], v24, s8, v[16:17]
	v_mad_u64_u32 v[88:89], s[36:37], v22, s8, v[16:17]
	v_mul_lo_u32 v16, v24, 48
	v_lshlrev_b32_e32 v24, 1, v98
	s_and_b32 s4, s4, 0x60
	v_cndmask_b32_e64 v157, 0, 1.0, vcc
	v_cmp_eq_u32_e32 vcc, 5, v98
	v_add3_u32 v89, s2, v16, v24
	v_mul_lo_u32 v16, v22, 48
	v_cndmask_b32_e64 v158, 0, 1.0, vcc
	v_cmp_eq_u32_e32 vcc, 4, v98
	v_add3_u32 v163, s2, v16, v24
	v_or_b32_e32 v16, s4, v98
	v_cndmask_b32_e64 v159, 0, 1.0, vcc
	v_cmp_eq_u32_e32 vcc, 3, v98
	v_mul_u32_u24_e32 v22, 0x220, v90
	v_lshl_add_u32 v24, v16, 1, s6
	v_or_b32_e32 v21, 1, v21
	v_mov_b32_e32 v7, v5
	v_mov_b32_e32 v5, v76
	v_or_b32_e32 v20, s5, v98
	v_cndmask_b32_e64 v160, 0, 1.0, vcc
	v_cmp_eq_u32_e32 vcc, 2, v98
	v_lshl_add_u32 v164, v22, 1, v24
	v_mul_u32_u24_e32 v22, 0x88, v21
	v_lshl_or_b32 v90, v90, 9, v16
	v_lshl_or_b32 v92, v21, 7, v16
	v_or_b32_e32 v16, 16, v98
	v_pk_mul_f32 v[48:49], v[48:49], v[0:1] op_sel_hi:[1,0]
	v_pk_mul_f32 v[50:51], v[50:51], v[14:15] op_sel_hi:[1,0]
	v_pk_mul_f32 v[54:55], v[54:55], v[14:15] op_sel_hi:[1,0]
	v_pk_mul_f32 v[56:57], v[56:57], v[0:1] op_sel_hi:[1,0]
	v_pk_mul_f32 v[70:71], v[12:13], v[14:15] op_sel_hi:[1,0]
	v_pk_mul_f32 v[72:73], v[6:7], v[0:1] op_sel_hi:[1,0]
	v_pk_mul_f32 v[74:75], v[2:3], v[14:15] op_sel_hi:[1,0]
	v_pk_mul_f32 v[76:77], v[4:5], v[0:1] op_sel_hi:[1,0]
	v_mul_u32_u24_e32 v20, 0x110, v20
	v_cndmask_b32_e64 v161, 0, 1.0, vcc
	v_cmp_eq_u32_e32 vcc, 1, v98
	v_lshl_add_u32 v165, v22, 1, v24
	v_mul_u32_u24_e32 v22, 48, v98
	v_mul_u32_u24_e32 v16, 0x90, v16
	v_readlane_b32 s2, v252, 15
	s_mov_b32 s31, 0
	v_sub_u32_e32 v103, 63, v91
	v_cvt_pk_bf16_f32 v0, v50, v51
	v_cvt_pk_bf16_f32 v1, v54, v55
	v_cvt_pk_bf16_f32 v2, v58, v59
	v_cvt_pk_bf16_f32 v3, v62, v63
	v_cvt_pk_bf16_f32 v4, v66, v67
	v_cvt_pk_bf16_f32 v5, v70, v71
	v_cvt_pk_bf16_f32 v6, v74, v75
	v_cvt_pk_bf16_f32 v7, v78, v79
	v_lshlrev_b32_e32 v142, 2, v8
	v_cvt_pk_bf16_f32 v8, v48, v49
	v_cvt_pk_bf16_f32 v9, v52, v53
	v_cvt_pk_bf16_f32 v10, v56, v57
	v_cvt_pk_bf16_f32 v11, v60, v61
	v_cvt_pk_bf16_f32 v12, v64, v65
	v_cvt_pk_bf16_f32 v13, v68, v69
	v_cvt_pk_bf16_f32 v14, v72, v73
	v_cvt_pk_bf16_f32 v15, v76, v77
	v_cndmask_b32_e64 v162, 0, 1.0, vcc
	v_cvt_pk_bf16_f32 v87, v147, s0
	v_add_u32_e32 v183, 0x110, v165
	v_add_u32_e32 v184, 0x220, v165
	v_or_b32_e32 v94, 0x100, v90
	v_or_b32_e32 v96, 0x180, v90
	v_add_u32_e32 v185, 0xff0, v165
	v_add_u32_e32 v186, 0x1100, v165
	v_add_u32_e32 v187, 0x1210, v165
	v_add_u32_e32 v188, 0x1320, v165
	v_or_b32_e32 v98, 0x800, v90
	v_or_b32_e32 v100, 0x880, v90
	v_or_b32_e32 v102, 0x900, v90
	v_or_b32_e32 v104, 0x980, v90
	v_add_u32_e32 v189, 0x20f0, v165
	v_add_u32_e32 v190, 0x2200, v165
	v_add_u32_e32 v191, 0x2310, v165
	v_add_u32_e32 v192, 0x2420, v165
	v_or_b32_e32 v106, 0x1000, v90
	v_or_b32_e32 v108, 0x1080, v90
	v_or_b32_e32 v110, 0x1100, v90
	v_or_b32_e32 v112, 0x1180, v90
	v_add_u32_e32 v193, 0x31f0, v165
	v_add_u32_e32 v194, 0x3300, v165
	v_add_u32_e32 v195, 0x3410, v165
	v_add_u32_e32 v196, 0x3520, v165
	v_or_b32_e32 v114, 0x1800, v90
	v_or_b32_e32 v116, 0x1880, v90
	v_or_b32_e32 v118, 0x1900, v90
	v_or_b32_e32 v120, 0x1980, v90
	s_or_b32 s30, s2, s30
	s_mov_b64 s[36:37], -1
	v_add_u32_e32 v197, v19, v25
	v_lshlrev_b32_e32 v132, 1, v18
	v_add_u32_e32 v198, v19, v20
	v_add_u32_e32 v199, v17, v22
	v_add_u32_e32 v200, v23, v16
	s_branch .LBB0_322
